# P2a kbar/conv: stores as global_store, loop-top waits count down to the prefetched loads only (store acknowledgements not waited)
# speedup vs baseline: 1.0071x; 1.0029x over previous
; __device__ __forceinline__ int opaque_tid() { int t = threadIdx.x; asm volatile("" : "+v"(t)); return t; }
; __device__ __forceinline__ void p2a_kbar(const Args& A, char* lds, int G) {
;     const int tid = opaque_tid(); const bf16* P0 = (const bf16*)(A.ws + WS_BIG); float* kbar = (float*)(A.ws + WS_KBAR); float* red = (float*)lds;
;     for (int item = blockIdx.x; item < NB * 16 * 8; item += G) {
;         const int b = item >> 7, h = (item >> 3) & 15, n = item & 7; const int c8 = tid & 7, rg = tid >> 3;
;         float acc[8];
; #pragma unroll
;         for (int e = 0; e < 8; ++e) acc[e] = 0.f;
; #pragma unroll
;         for (int i = 0; i < 4; ++i) { const bf16x8 kv = *(const bf16x8*)(P0 + (size_t)(b * SEQL + n * 256 + rg + 64 * i) * LD0 + C0_K + h * 64 + c8 * 8);
; __device__ __forceinline__ Args get_args(const unsigned char* lds) {
;     ...
;     for (int i = 0; i < 29; ++i) { const unsigned long long v = p[i]; const unsigned lo = __builtin_amdgcn_readfirstlane((unsigned)v), hi = __builtin_amdgcn_readfirstlane((unsigned)(v >> 32));
;         const unsigned long long w = ((unsigned long long)hi << 32) | lo; if (i < 27) a.in[i] = (const float*)w; else if (i == 27) a.out = (float*)w; else a.ws = (unsigned char*)w; }
.LBB0_592:
	s_or_b64 exec, exec, s[36:37]
	s_add_i32 s0, 0, 0x20438
	v_mov_b32_e32 v0, s0
	s_add_i32 s0, 0, 0x204d8
	v_mov_b32_e32 v4, s0
	s_waitcnt lgkmcnt(0)
	s_barrier
	ds_read2_b64 v[0:3], v0 offset1:1
	ds_read2_b64 v[4:7], v4 offset1:1
	s_mov_b32 s7, 0
	s_cmpk_gt_i32 s2, 0x3ff
	s_waitcnt lgkmcnt(0)
	v_readfirstlane_b32 s15, v1
	v_readfirstlane_b32 s14, v0
	v_readfirstlane_b32 s13, v3
	v_readfirstlane_b32 s12, v2
	v_readfirstlane_b32 s11, v5
	v_readfirstlane_b32 s10, v4
	v_readfirstlane_b32 s9, v7
	v_readfirstlane_b32 s8, v6
	v_mov_b32_e32 v2, v220
	s_cbranch_scc1 .LBB0_597
	v_ashrrev_i32_e32 v6, 3, v2
	s_movk_i32 s0, 0x104
	s_ashr_i32 s3, s2, 31
	v_mul_lo_u32 v4, v6, s0
	s_lshl_b64 s[0:1], s[2:3], 8
	v_and_b32_e32 v3, 7, v2
	s_add_u32 s0, s8, s0
	v_lshlrev_b32_e32 v0, 3, v3
	v_lshlrev_b32_e32 v9, 5, v3
	v_ashrrev_i32_e32 v3, 31, v2
	s_addc_u32 s1, s9, s1
	v_cmp_gt_i32_e64 s[4:5], 64, v2
	v_lshl_add_u32 v7, v2, 2, 0
	v_lshl_add_u64 v[2:3], v[2:3], 2, s[0:1]
	s_mov_b64 s[0:1], 0x210000
	v_add_u32_e32 v8, 0, v4
	v_lshl_add_u64 v[2:3], v[2:3], 0, s[0:1]
	s_ashr_i32 s1, s38, 31
	s_mov_b32 s0, s38
	v_mov_b32_e32 v1, 0
	s_lshl_b64 s[16:17], s[0:1], 8
	s_lshl_b32 s0, s2, 3
	s_lshl_b32 s1, s2, 8
	s_lshl_b32 s3, s38, 8
	s_lshl_b32 s20, s2, 4
	s_lshl_b32 s21, s38, 4
	s_movk_i32 s22, 0x3400
	v_mov_b64_e32 v[4:5], s[8:9]
	v_lshlrev_b32_e32 v0, 1, v0
	v_add_u32_e32 v8, v8, v9
	s_mov_b32 s23, s2
	s_and_b32 s6, s20, 0xfffff800
	s_and_b32 s18, s1, 0x700
	s_or_b32 s6, s6, s18
	v_add_u32_e32 v9, s6, v6
	s_and_b32 s6, s0, 0x3c0
	v_mad_i64_i32 v[34:35], s[18:19], v9, s22, v[4:5]
	s_lshl_b32 s6, s6, 1
	v_lshl_add_u64 v[34:35], v[34:35], 0, s[6:7]
	v_add_u32_e32 v38, 64, v9
	v_lshl_add_u64 v[34:35], v[34:35], 0, v[0:1]
	v_mad_i64_i32 v[38:39], s[18:19], v38, s22, v[4:5]
	v_add_co_u32_e32 v34, vcc, 0x1b02000, v34
	v_lshl_add_u64 v[38:39], v[38:39], 0, s[6:7]
	v_add_u32_e32 v42, 0x80, v9
	v_addc_co_u32_e32 v35, vcc, 0, v35, vcc
	v_lshl_add_u64 v[38:39], v[38:39], 0, v[0:1]
	v_mad_i64_i32 v[42:43], s[18:19], v42, s22, v[4:5]
	v_add_co_u32_e32 v38, vcc, 0x1b02000, v38
	v_lshl_add_u64 v[42:43], v[42:43], 0, s[6:7]
	v_add_u32_e32 v9, 0xc0, v9
	v_addc_co_u32_e32 v39, vcc, 0, v39, vcc
	v_lshl_add_u64 v[42:43], v[42:43], 0, v[0:1]
	v_mad_i64_i32 v[46:47], s[18:19], v9, s22, v[4:5]
	v_add_co_u32_e32 v42, vcc, 0x1b02000, v42
	v_lshl_add_u64 v[46:47], v[46:47], 0, s[6:7]
	global_load_dwordx4 v[34:37], v[34:35], off offset:1024
	v_addc_co_u32_e32 v43, vcc, 0, v43, vcc
	v_lshl_add_u64 v[46:47], v[46:47], 0, v[0:1]
	global_load_dwordx4 v[38:41], v[38:39], off offset:1024
	v_add_co_u32_e32 v46, vcc, 0x1b02000, v46
	global_load_dwordx4 v[42:45], v[42:43], off offset:1024
	s_nop 0
	v_addc_co_u32_e32 v47, vcc, 0, v47, vcc
	global_load_dwordx4 v[46:49], v[46:47], off offset:1024
	s_waitcnt vmcnt(0)
	s_branch .LBB0_595

; __device__ __forceinline__ float bf2f(unsigned short h) { return __uint_as_float(((unsigned)h) << 16); }
; __device__ __forceinline__ void p2a_kbar(const Args& A, char* lds, int G) {
;     ...
;         for (int i = 0; i < 4; ++i) { const bf16x8 kv = *(const bf16x8*)(P0 + (size_t)(b * SEQL + n * 256 + rg + 64 * i) * LD0 + C0_K + h * 64 + c8 * 8);
; #pragma unroll
;             for (int e = 0; e < 8; ++e) acc[e] += bf2f((unsigned short)kv[e]); }
;         __syncthreads();
; #pragma unroll
;         for (int e = 0; e < 8; ++e) red[rg * 65 + c8 * 8 + e] = acc[e];
.LBB0_595:
	s_waitcnt lgkmcnt(0)
	s_barrier
	s_cmp_lg_u64 s[4:5], 0
	s_cbranch_scc1 .Lkb_w0
	s_waitcnt vmcnt(0)
	s_branch .Lkb_wj
.Lkb_w0:
	s_waitcnt vmcnt(1)
.Lkb_wj:
	v_mov_b32_e32 v10, v34
	v_mov_b32_e32 v11, v35
	v_mov_b32_e32 v12, v36
	v_mov_b32_e32 v13, v37
	v_mov_b32_e32 v14, v38
	v_mov_b32_e32 v15, v39
	v_mov_b32_e32 v16, v40
	v_mov_b32_e32 v17, v41
	v_mov_b32_e32 v18, v42
	v_mov_b32_e32 v19, v43
	v_mov_b32_e32 v20, v44
	v_mov_b32_e32 v21, v45
	v_mov_b32_e32 v22, v46
	v_mov_b32_e32 v23, v47
	v_mov_b32_e32 v24, v48
	v_mov_b32_e32 v25, v49
	v_and_b32_e32 v27, 0xffff0000, v10
	v_lshlrev_b32_e32 v26, 16, v10
	v_and_b32_e32 v29, 0xffff0000, v11
	v_lshlrev_b32_e32 v28, 16, v11
	v_and_b32_e32 v11, 0xffff0000, v12
	v_lshlrev_b32_e32 v10, 16, v12
	v_and_b32_e32 v31, 0xffff0000, v13
	v_lshlrev_b32_e32 v30, 16, v13
	v_pk_add_f32 v[12:13], v[26:27], 0 op_sel_hi:[1,0]
	v_and_b32_e32 v27, 0xffff0000, v14
	v_lshlrev_b32_e32 v26, 16, v14
	v_and_b32_e32 v33, 0xffff0000, v15
	v_lshlrev_b32_e32 v32, 16, v15
	v_pk_add_f32 v[10:11], v[10:11], 0 op_sel_hi:[1,0]
	v_and_b32_e32 v15, 0xffff0000, v16
	v_lshlrev_b32_e32 v14, 16, v16
	v_pk_add_f32 v[28:29], v[28:29], 0 op_sel_hi:[1,0]
	v_pk_add_f32 v[12:13], v[12:13], v[26:27]
	v_and_b32_e32 v27, 0xffff0000, v18
	v_lshlrev_b32_e32 v26, 16, v18
	v_pk_add_f32 v[10:11], v[10:11], v[14:15]
	v_and_b32_e32 v15, 0xffff0000, v20
	v_lshlrev_b32_e32 v14, 16, v20
	v_pk_add_f32 v[28:29], v[28:29], v[32:33]
	v_and_b32_e32 v33, 0xffff0000, v19
	v_lshlrev_b32_e32 v32, 16, v19
	v_pk_add_f32 v[12:13], v[12:13], v[26:27]
	v_and_b32_e32 v19, 0xffff0000, v22
	v_lshlrev_b32_e32 v18, 16, v22
	v_pk_add_f32 v[10:11], v[10:11], v[14:15]
	v_and_b32_e32 v15, 0xffff0000, v24
	v_lshlrev_b32_e32 v14, 16, v24
	v_pk_add_f32 v[26:27], v[28:29], v[32:33]
	v_and_b32_e32 v29, 0xffff0000, v23
	v_lshlrev_b32_e32 v28, 16, v23
	v_pk_add_f32 v[12:13], v[12:13], v[18:19]
	v_pk_add_f32 v[10:11], v[10:11], v[14:15]
	v_pk_add_f32 v[30:31], v[30:31], 0 op_sel_hi:[1,0]
	v_pk_add_f32 v[18:19], v[26:27], v[28:29]
	ds_write2_b32 v8, v12, v13 offset1:1
	ds_write2_b32 v8, v18, v19 offset0:2 offset1:3
	ds_write2_b32 v8, v10, v11 offset0:4 offset1:5
	v_and_b32_e32 v11, 0xffff0000, v17
	v_lshlrev_b32_e32 v10, 16, v17
	v_pk_add_f32 v[10:11], v[30:31], v[10:11]
	v_and_b32_e32 v13, 0xffff0000, v21
	v_lshlrev_b32_e32 v12, 16, v21
	v_pk_add_f32 v[10:11], v[10:11], v[12:13]
	v_and_b32_e32 v13, 0xffff0000, v25
	v_lshlrev_b32_e32 v12, 16, v25
	v_pk_add_f32 v[10:11], v[10:11], v[12:13]
	ds_write2_b32 v8, v10, v11 offset0:6 offset1:7
	s_add_i32 s98, s23, s38
	s_cmpk_lt_i32 s98, 0x400
	s_cbranch_scc0 .Lkb_nopf
	s_add_i32 s99, s20, s21
	s_add_i32 s100, s1, s3
	s_add_i32 s101, s0, s44
	s_and_b32 s6, s99, 0xfffff800
	s_and_b32 s18, s100, 0x700
	s_or_b32 s6, s6, s18
	v_add_u32_e32 v9, s6, v6
	s_and_b32 s6, s101, 0x3c0
	v_mad_i64_i32 v[34:35], s[18:19], v9, s22, v[4:5]
	s_lshl_b32 s6, s6, 1
	v_lshl_add_u64 v[34:35], v[34:35], 0, s[6:7]
	v_add_u32_e32 v38, 64, v9
	v_lshl_add_u64 v[34:35], v[34:35], 0, v[0:1]
	v_mad_i64_i32 v[38:39], s[18:19], v38, s22, v[4:5]
	v_add_co_u32_e32 v34, vcc, 0x1b02000, v34
	v_lshl_add_u64 v[38:39], v[38:39], 0, s[6:7]
	v_add_u32_e32 v42, 0x80, v9
	v_addc_co_u32_e32 v35, vcc, 0, v35, vcc
	v_lshl_add_u64 v[38:39], v[38:39], 0, v[0:1]
	v_mad_i64_i32 v[42:43], s[18:19], v42, s22, v[4:5]
	v_add_co_u32_e32 v38, vcc, 0x1b02000, v38
	v_lshl_add_u64 v[42:43], v[42:43], 0, s[6:7]
	v_add_u32_e32 v9, 0xc0, v9
	v_addc_co_u32_e32 v39, vcc, 0, v39, vcc
	v_lshl_add_u64 v[42:43], v[42:43], 0, v[0:1]
	v_mad_i64_i32 v[46:47], s[18:19], v9, s22, v[4:5]
	v_add_co_u32_e32 v42, vcc, 0x1b02000, v42
	v_lshl_add_u64 v[46:47], v[46:47], 0, s[6:7]
	global_load_dwordx4 v[34:37], v[34:35], off offset:1024
	v_addc_co_u32_e32 v43, vcc, 0, v43, vcc
	v_lshl_add_u64 v[46:47], v[46:47], 0, v[0:1]
	global_load_dwordx4 v[38:41], v[38:39], off offset:1024
	v_add_co_u32_e32 v46, vcc, 0x1b02000, v46
	global_load_dwordx4 v[42:45], v[42:43], off offset:1024
	s_nop 0
	v_addc_co_u32_e32 v47, vcc, 0, v47, vcc
	global_load_dwordx4 v[46:49], v[46:47], off offset:1024
; __device__ __forceinline__ void p2a_kbar(const Args& A, char* lds, int G) {
;     ...
;         __syncthreads();
;         if (tid < 64) { float s = 0.f; for (int r = 0; r < 64; ++r) s += red[r * 65 + tid]; kbar[(size_t)item * 64 + tid] = s * (1.f / 256.f); }
.Lkb_nopf:
	s_waitcnt lgkmcnt(0)
	s_barrier
	s_and_saveexec_b64 s[18:19], s[4:5]
	s_cbranch_execz .LBB0_594
	ds_read2_b32 v[10:11], v7 offset1:65
	ds_read2_b32 v[12:13], v7 offset0:130 offset1:195
	v_add_u32_e32 v9, 0x400, v7
	ds_read2_b32 v[14:15], v9 offset0:4 offset1:69
	ds_read2_b32 v[16:17], v9 offset0:134 offset1:199
	s_waitcnt lgkmcnt(3)
	v_add_f32_e32 v9, 0, v10
	v_add_f32_e32 v9, v9, v11
	s_waitcnt lgkmcnt(2)
	v_add_f32_e32 v9, v9, v12
	v_add_u32_e32 v12, 0x800, v7
	v_add_f32_e32 v9, v9, v13
	ds_read2_b32 v[10:11], v12 offset0:8 offset1:73
	s_waitcnt lgkmcnt(2)
	v_add_f32_e32 v9, v9, v14
	v_add_f32_e32 v9, v9, v15
	s_waitcnt lgkmcnt(1)
	v_add_f32_e32 v9, v9, v16
	v_add_f32_e32 v9, v9, v17
	ds_read2_b32 v[12:13], v12 offset0:138 offset1:203
	s_waitcnt lgkmcnt(1)
	v_add_f32_e32 v9, v9, v10
	v_add_u32_e32 v10, 0xc00, v7
	ds_read2_b32 v[14:15], v10 offset0:12 offset1:77
	v_add_f32_e32 v9, v9, v11
	ds_read2_b32 v[10:11], v10 offset0:142 offset1:207
	s_waitcnt lgkmcnt(2)
	v_add_f32_e32 v9, v9, v12
	v_add_f32_e32 v9, v9, v13
	s_waitcnt lgkmcnt(1)
	v_add_f32_e32 v9, v9, v14
	v_add_f32_e32 v9, v9, v15
	s_waitcnt lgkmcnt(0)
	v_add_f32_e32 v9, v9, v10
	v_add_u32_e32 v10, 0x1000, v7
	ds_read2_b32 v[12:13], v10 offset0:16 offset1:81
	v_add_f32_e32 v9, v9, v11
	ds_read2_b32 v[10:11], v10 offset0:146 offset1:211
	v_add_u32_e32 v16, 0x1400, v7
	ds_read2_b32 v[14:15], v16 offset0:20 offset1:85
	s_waitcnt lgkmcnt(2)
	v_add_f32_e32 v9, v9, v12
	v_add_f32_e32 v9, v9, v13
	s_waitcnt lgkmcnt(1)
	v_add_f32_e32 v9, v9, v10
	v_add_f32_e32 v9, v9, v11
	ds_read2_b32 v[10:11], v16 offset0:150 offset1:215
	s_waitcnt lgkmcnt(1)
	v_add_f32_e32 v9, v9, v14
	v_add_u32_e32 v14, 0x1800, v7
	ds_read2_b32 v[12:13], v14 offset0:24 offset1:89
	v_add_f32_e32 v9, v9, v15
	s_waitcnt lgkmcnt(1)
	v_add_f32_e32 v9, v9, v10
	ds_read2_b32 v[14:15], v14 offset0:154 offset1:219
	v_add_f32_e32 v9, v9, v11
	s_waitcnt lgkmcnt(1)
	v_add_f32_e32 v9, v9, v12
	v_add_u32_e32 v12, 0x1c00, v7
	ds_read2_b32 v[10:11], v12 offset0:28 offset1:93
	v_add_f32_e32 v9, v9, v13
	ds_read2_b32 v[12:13], v12 offset0:158 offset1:223
	s_waitcnt lgkmcnt(2)
	v_add_f32_e32 v9, v9, v14
	v_add_u32_e32 v16, 0x2000, v7
	v_add_f32_e32 v9, v9, v15
	ds_read2_b32 v[14:15], v16 offset0:32 offset1:97
	s_waitcnt lgkmcnt(2)
	v_add_f32_e32 v9, v9, v10
	v_add_f32_e32 v9, v9, v11
	s_waitcnt lgkmcnt(1)
	v_add_f32_e32 v9, v9, v12
	v_add_f32_e32 v9, v9, v13
	ds_read2_b32 v[10:11], v16 offset0:162 offset1:227
	s_waitcnt lgkmcnt(1)
	v_add_f32_e32 v9, v9, v14
	v_add_u32_e32 v14, 0x2400, v7
	ds_read2_b32 v[12:13], v14 offset0:36 offset1:101
	v_add_f32_e32 v9, v9, v15
	s_waitcnt lgkmcnt(1)
	v_add_f32_e32 v9, v9, v10
	ds_read2_b32 v[14:15], v14 offset0:166 offset1:231
	v_add_f32_e32 v9, v9, v11
	s_waitcnt lgkmcnt(1)
	v_add_f32_e32 v9, v9, v12
	v_add_u32_e32 v12, 0x2800, v7
	ds_read2_b32 v[10:11], v12 offset0:40 offset1:105
	v_add_f32_e32 v9, v9, v13
	ds_read2_b32 v[12:13], v12 offset0:170 offset1:235
	s_waitcnt lgkmcnt(2)
	v_add_f32_e32 v9, v9, v14
	v_add_u32_e32 v16, 0x2c00, v7
	v_add_f32_e32 v9, v9, v15
	ds_read2_b32 v[14:15], v16 offset0:44 offset1:109
	s_waitcnt lgkmcnt(2)
	v_add_f32_e32 v9, v9, v10
	v_add_f32_e32 v9, v9, v11
	s_waitcnt lgkmcnt(1)
	v_add_f32_e32 v9, v9, v12
	v_add_f32_e32 v9, v9, v13
	ds_read2_b32 v[10:11], v16 offset0:174 offset1:239
	s_waitcnt lgkmcnt(1)
	v_add_f32_e32 v9, v9, v14
	v_add_u32_e32 v14, 0x3000, v7
	ds_read2_b32 v[12:13], v14 offset0:48 offset1:113
	v_add_f32_e32 v9, v9, v15
	s_waitcnt lgkmcnt(1)
	v_add_f32_e32 v9, v9, v10
	ds_read2_b32 v[14:15], v14 offset0:178 offset1:243
	v_add_f32_e32 v9, v9, v11
	s_waitcnt lgkmcnt(1)
	v_add_f32_e32 v9, v9, v12
	v_add_u32_e32 v12, 0x3400, v7
	ds_read2_b32 v[10:11], v12 offset0:52 offset1:117
	v_add_f32_e32 v9, v9, v13
	ds_read2_b32 v[12:13], v12 offset0:182 offset1:247
	s_waitcnt lgkmcnt(2)
	v_add_f32_e32 v9, v9, v14
	v_add_u32_e32 v16, 0x3800, v7
	v_add_f32_e32 v9, v9, v15
	ds_read2_b32 v[14:15], v16 offset0:56 offset1:121
	s_waitcnt lgkmcnt(2)
	v_add_f32_e32 v9, v9, v10
	v_add_f32_e32 v9, v9, v11
	s_waitcnt lgkmcnt(1)
	v_add_f32_e32 v9, v9, v12
	v_add_f32_e32 v9, v9, v13
	ds_read2_b32 v[10:11], v16 offset0:186 offset1:251
	s_waitcnt lgkmcnt(1)
	v_add_f32_e32 v9, v9, v14
	v_add_u32_e32 v14, 0x3c00, v7
	ds_read2_b32 v[12:13], v14 offset0:60 offset1:125
	v_add_f32_e32 v9, v9, v15
	ds_read2_b32 v[14:15], v14 offset0:190 offset1:255
	s_waitcnt lgkmcnt(2)
	v_add_f32_e32 v9, v9, v10
	v_add_f32_e32 v9, v9, v11
	s_waitcnt lgkmcnt(1)
	v_add_f32_e32 v9, v9, v12
	v_add_f32_e32 v9, v9, v13
	s_waitcnt lgkmcnt(0)
	v_add_f32_e32 v9, v9, v14
	v_add_f32_e32 v9, v9, v15
	v_mul_f32_e32 v9, 0x3b800000, v9
	global_store_dword v[2:3], v9, off
	s_branch .LBB0_594

; __device__ __forceinline__ void p2a_conv(const Args& A, int G) {
;     ...
;         if (tb > 0) { r0 = *(const bf16x8*)(P0 + (size_t)(m0 - 3) * LD0 + C0_XBC + ch); r1 = *(const bf16x8*)(P0 + (size_t)(m0 - 2) * LD0 + C0_XBC + ch); r2 = *(const bf16x8*)(P0 + (size_t)(m0 - 1) * LD0 + C0_XBC + ch); }
; #pragma unroll 1
;         for (int i0 = 0; i0 < 32; i0 += 8) { bf16x8 rr[8];
; #pragma unroll
;         for (int i = 0; i < 8; ++i) rr[i] = *(const bf16x8*)(P0 + (size_t)(m0 + i0 + i) * LD0 + C0_XBC + ch);
; #pragma unroll
;         for (int ii = 0; ii < 8; ++ii) { const int i = i0 + ii; const bf16x8 r3 = rr[ii]; float o[8];
.LBB0_602:
	s_or_b64 exec, exec, s[10:11]
	v_readfirstlane_b32 s98, v125
	s_nop 0
	s_mul_hi_u32 s101, s98, s1
	s_mul_i32 s100, s98, s1
	s_add_u32 s100, s100, s8
	s_addc_u32 s101, s101, s9
	s_add_u32 s100, s100, 0x1000
	s_addc_u32 s101, s101, 0
	global_load_dwordx4 v[210:213], v58, s[100:101] offset:2048
	s_add_u32 s98, s100, 0x3400
	s_addc_u32 s99, s101, 0
	global_load_dwordx4 v[214:217], v58, s[98:99] offset:2048
	s_add_u32 s98, s100, 0x6800
	s_addc_u32 s99, s101, 0
	global_load_dwordx4 v[222:225], v58, s[98:99] offset:2048
	s_add_u32 s98, s100, 0x9c00
	s_addc_u32 s99, s101, 0
	global_load_dwordx4 v[226:229], v58, s[98:99] offset:2048
	s_add_u32 s98, s100, 0xd000
	s_addc_u32 s99, s101, 0
	global_load_dwordx4 v[230:233], v58, s[98:99] offset:2048
	s_add_u32 s98, s100, 0x10400
	s_addc_u32 s99, s101, 0
	global_load_dwordx4 v[234:237], v58, s[98:99] offset:2048
	s_add_u32 s98, s100, 0x13800
	s_addc_u32 s99, s101, 0
	global_load_dwordx4 v[238:241], v58, s[98:99] offset:2048
	s_add_u32 s98, s100, 0x16c00
	s_addc_u32 s99, s101, 0
	global_load_dwordx4 v[242:245], v58, s[98:99] offset:2048
	s_waitcnt vmcnt(0)
	s_mov_b32 s4, -8
.LBB0_603:
	v_add_u32_e32 v41, s4, v125
	v_mov_b64_e32 v[60:61], s[8:9]
	s_waitcnt vmcnt(8) lgkmcnt(0)
	v_and_b32_e32 v67, 0xffff0000, v42
	v_lshlrev_b32_e32 v66, 16, v42
	v_and_b32_e32 v63, 0xffff0000, v50
	v_lshlrev_b32_e32 v62, 16, v50
	v_and_b32_e32 v71, 0xffff0000, v43
	v_lshlrev_b32_e32 v70, 16, v43
	v_and_b32_e32 v43, 0xffff0000, v51
	v_lshlrev_b32_e32 v42, 16, v51
	v_and_b32_e32 v51, 0xffff0000, v48
	v_lshlrev_b32_e32 v50, 16, v48
	v_and_b32_e32 v77, 0xffff0000, v45
	v_lshlrev_b32_e32 v76, 16, v45
	v_add_u32_e32 v48, 8, v41
	v_and_b32_e32 v65, 0xffff0000, v46
	v_lshlrev_b32_e32 v64, 16, v46
	v_and_b32_e32 v69, 0xffff0000, v47
	v_lshlrev_b32_e32 v68, 16, v47
	v_and_b32_e32 v73, 0xffff0000, v44
	v_lshlrev_b32_e32 v72, 16, v44
	v_and_b32_e32 v75, 0xffff0000, v49
	v_lshlrev_b32_e32 v74, 16, v49
	v_pk_fma_f32 v[66:67], v[0:1], v[66:67], v[32:33]
	v_pk_fma_f32 v[70:71], v[2:3], v[70:71], v[34:35]
	v_pk_fma_f32 v[76:77], v[6:7], v[76:77], v[38:39]
	v_mad_i64_i32 v[100:101], s[10:11], v48, s1, v[60:61]
	v_and_b32_e32 v47, 0xffff0000, v52
	v_lshlrev_b32_e32 v46, 16, v52
	v_add_u32_e32 v52, 9, v41
	v_add_u32_e32 v78, 10, v41
	v_pk_fma_f32 v[72:73], v[4:5], v[72:73], v[36:37]
	v_pk_fma_f32 v[90:91], v[0:1], v[64:65], v[32:33]
	v_pk_fma_f32 v[92:93], v[2:3], v[68:69], v[34:35]
	v_pk_fma_f32 v[64:65], v[8:9], v[64:65], v[66:67]
	v_pk_fma_f32 v[66:67], v[10:11], v[68:69], v[70:71]
	v_pk_fma_f32 v[68:69], v[14:15], v[74:75], v[76:77]
	v_lshl_add_u64 v[76:77], v[100:101], 0, v[58:59]
	v_pk_fma_f32 v[94:95], v[4:5], v[50:51], v[36:37]
	v_mad_i64_i32 v[102:103], s[10:11], v52, s1, v[60:61]
	v_ashrrev_i32_e32 v79, 31, v78
	v_pk_fma_f32 v[50:51], v[12:13], v[50:51], v[72:73]
	v_add_co_u32_e32 v76, vcc, 0x1000, v76
	v_add_u32_e32 v82, 12, v41
	v_pk_fma_f32 v[106:107], v[4:5], v[46:47], v[36:37]
	v_pk_fma_f32 v[120:121], v[10:11], v[42:43], v[92:93]
	v_pk_fma_f32 v[122:123], v[12:13], v[46:47], v[94:95]
	v_lshl_add_u64 v[92:93], v[102:103], 0, v[58:59]
	v_pk_fma_f32 v[134:135], v[20:21], v[46:47], v[50:51]
	v_lshlrev_b64 v[46:47], 12, v[78:79]
	v_addc_co_u32_e32 v77, vcc, 0, v77, vcc
	v_mad_i64_i32 v[108:109], s[10:11], v78, s1, v[60:61]
	v_ashrrev_i32_e32 v83, 31, v82
	v_lshl_add_u64 v[70:71], v[56:57], 0, v[46:47]
	v_add_co_u32_e32 v46, vcc, 0x1000, v92
	v_add_u32_e32 v80, 11, v41
	v_add_u32_e32 v84, 13, v41
	v_lshl_add_u64 v[94:95], v[108:109], 0, v[58:59]
	v_lshlrev_b64 v[50:51], 12, v[82:83]
	v_addc_co_u32_e32 v47, vcc, 0, v93, vcc
	v_and_b32_e32 v45, 0xffff0000, v53
	v_lshlrev_b32_e32 v44, 16, v53
	v_pk_fma_f32 v[96:97], v[6:7], v[74:75], v[38:39]
	v_ashrrev_i32_e32 v53, 31, v52
	v_mad_i64_i32 v[110:111], s[10:11], v80, s1, v[60:61]
	v_ashrrev_i32_e32 v85, 31, v84
	v_pk_fma_f32 v[132:133], v[18:19], v[42:43], v[66:67]
	v_lshl_add_u64 v[66:67], v[56:57], 0, v[50:51]
	v_add_co_u32_e32 v50, vcc, 0x1000, v94
	v_pk_fma_f32 v[112:113], v[6:7], v[44:45], v[38:39]
	v_pk_fma_f32 v[96:97], v[14:15], v[44:45], v[96:97]
	v_lshl_add_u64 v[100:101], v[110:111], 0, v[58:59]
	v_pk_fma_f32 v[136:137], v[22:23], v[44:45], v[68:69]
	v_lshlrev_b64 v[44:45], 12, v[52:53]
	v_lshlrev_b64 v[52:53], 12, v[84:85]
	v_addc_co_u32_e32 v51, vcc, 0, v95, vcc
	v_ashrrev_i32_e32 v49, 31, v48
	v_ashrrev_i32_e32 v81, 31, v80
	v_mad_i64_i32 v[114:115], s[10:11], v82, s1, v[60:61]
	v_pk_fma_f32 v[130:131], v[16:17], v[62:63], v[64:65]
	v_lshl_add_u64 v[64:65], v[56:57], 0, v[52:53]
	v_add_co_u32_e32 v52, vcc, 0x1000, v100
	v_pk_fma_f32 v[104:105], v[2:3], v[42:43], v[34:35]
	v_lshl_add_u64 v[108:109], v[114:115], 0, v[58:59]
	v_lshlrev_b64 v[42:43], 12, v[48:49]
	v_lshlrev_b64 v[48:49], 12, v[80:81]
	v_addc_co_u32_e32 v53, vcc, 0, v101, vcc
	v_mad_i64_i32 v[116:117], s[10:11], v84, s1, v[60:61]
	v_lshl_add_u64 v[74:75], v[56:57], 0, v[42:43]
	v_lshl_add_u64 v[72:73], v[56:57], 0, v[44:45]
	v_lshl_add_u64 v[68:69], v[56:57], 0, v[48:49]
	v_mov_b32_e32 v42, v210
	v_mov_b32_e32 v43, v211
	v_mov_b32_e32 v44, v212
	v_mov_b32_e32 v45, v213
	v_mov_b32_e32 v100, v226
	v_mov_b32_e32 v101, v227
	v_mov_b32_e32 v102, v228
	v_mov_b32_e32 v103, v229
	v_mov_b32_e32 v92, v222
	v_mov_b32_e32 v93, v223
	v_mov_b32_e32 v94, v224
	v_mov_b32_e32 v95, v225
	v_add_co_u32_e32 v50, vcc, 0x1000, v108
	v_mov_b32_e32 v46, v214
	v_mov_b32_e32 v47, v215
	v_mov_b32_e32 v48, v216
	v_mov_b32_e32 v49, v217
	v_add_u32_e32 v86, 14, v41
	v_lshl_add_u64 v[110:111], v[116:117], 0, v[58:59]
	v_addc_co_u32_e32 v51, vcc, 0, v109, vcc
	v_mad_i64_i32 v[118:119], s[10:11], v86, s1, v[60:61]
	v_add_co_u32_e32 v52, vcc, 0x1000, v110
	v_add_u32_e32 v88, 15, v41
	v_lshl_add_u64 v[114:115], v[118:119], 0, v[58:59]
	v_addc_co_u32_e32 v53, vcc, 0, v111, vcc
	v_ashrrev_i32_e32 v87, 31, v86
	v_ashrrev_i32_e32 v89, 31, v88
	v_mad_i64_i32 v[60:61], s[10:11], v88, s1, v[60:61]
	v_add_co_u32_e32 v76, vcc, 0x1000, v114
	v_lshl_add_u64 v[126:127], v[60:61], 0, v[58:59]
	v_lshlrev_b64 v[60:61], 12, v[86:87]
	v_lshlrev_b64 v[78:79], 12, v[88:89]
	v_mov_b32_e32 v108, v230
	v_mov_b32_e32 v109, v231
	v_mov_b32_e32 v110, v232
	v_mov_b32_e32 v111, v233
	v_mov_b32_e32 v116, v234
	v_mov_b32_e32 v117, v235
	v_mov_b32_e32 v118, v236
	v_mov_b32_e32 v119, v237
	v_addc_co_u32_e32 v77, vcc, 0, v115, vcc
	v_pk_fma_f32 v[98:99], v[0:1], v[62:63], v[32:33]
	v_pk_fma_f32 v[90:91], v[8:9], v[62:63], v[90:91]
	v_lshl_add_u64 v[62:63], v[56:57], 0, v[60:61]
	v_lshl_add_u64 v[60:61], v[56:57], 0, v[78:79]
	v_add_co_u32_e32 v78, vcc, 0x1000, v126
	s_add_i32 s4, s4, 8
	s_nop 0
	v_addc_co_u32_e32 v79, vcc, 0, v127, vcc
	v_mov_b32_e32 v126, v238
	v_mov_b32_e32 v127, v239
	v_mov_b32_e32 v128, v240
	v_mov_b32_e32 v129, v241
	v_mov_b32_e32 v50, v242
	v_mov_b32_e32 v51, v243
	v_mov_b32_e32 v52, v244
	v_mov_b32_e32 v53, v245
	s_cmp_gt_u32 s4, 23
	s_cbranch_scc1 .Lcv_nopf
; __device__ __forceinline__ float bf2f(unsigned short h) { return __uint_as_float(((unsigned)h) << 16); }
; __device__ __forceinline__ float silu_f(float x) { return x * __builtin_amdgcn_rcpf(1.f + __expf(-x)); }
; __device__ __forceinline__ void p2a_conv(const Args& A, int G) {
;     ...
;         for (int i0 = 0; i0 < 32; i0 += 8) { bf16x8 rr[8];
; #pragma unroll
;         for (int i = 0; i < 8; ++i) rr[i] = *(const bf16x8*)(P0 + (size_t)(m0 + i0 + i) * LD0 + C0_XBC + ch);
; #pragma unroll
;         for (int ii = 0; ii < 8; ++ii) { const int i = i0 + ii; const bf16x8 r3 = rr[ii]; float o[8];
; #pragma unroll
;             for (int e = 0; e < 8; ++e) { const float a = bs[e] + w[0][e] * bf2f((unsigned short)r0[e]) + w[1][e] * bf2f((unsigned short)r1[e]) + w[2][e] * bf2f((unsigned short)r2[e]) + w[3][e] * bf2f((unsigned short)r3[e]); o[e] = silu_f(a); }
	s_add_u32 s100, s100, 0x1a000
	s_addc_u32 s101, s101, 0
	global_load_dwordx4 v[210:213], v58, s[100:101] offset:2048
	s_add_u32 s98, s100, 0x3400
	s_addc_u32 s99, s101, 0
	global_load_dwordx4 v[214:217], v58, s[98:99] offset:2048
	s_add_u32 s98, s100, 0x6800
	s_addc_u32 s99, s101, 0
	global_load_dwordx4 v[222:225], v58, s[98:99] offset:2048
	s_add_u32 s98, s100, 0x9c00
	s_addc_u32 s99, s101, 0
	global_load_dwordx4 v[226:229], v58, s[98:99] offset:2048
	s_add_u32 s98, s100, 0xd000
	s_addc_u32 s99, s101, 0
	global_load_dwordx4 v[230:233], v58, s[98:99] offset:2048
	s_add_u32 s98, s100, 0x10400
	s_addc_u32 s99, s101, 0
	global_load_dwordx4 v[234:237], v58, s[98:99] offset:2048
	s_add_u32 s98, s100, 0x13800
	s_addc_u32 s99, s101, 0
	global_load_dwordx4 v[238:241], v58, s[98:99] offset:2048
	s_add_u32 s98, s100, 0x16c00
	s_addc_u32 s99, s101, 0
	global_load_dwordx4 v[242:245], v58, s[98:99] offset:2048
.Lcv_nopf:
	s_cmp_gt_u32 s4, 23
	s_waitcnt lgkmcnt(0)
	v_and_b32_e32 v85, 0xffff0000, v42
	v_lshlrev_b32_e32 v84, 16, v42
	v_and_b32_e32 v87, 0xffff0000, v43
	v_lshlrev_b32_e32 v86, 16, v43
	v_and_b32_e32 v43, 0xffff0000, v44
	v_lshlrev_b32_e32 v42, 16, v44
	v_and_b32_e32 v89, 0xffff0000, v45
	v_lshlrev_b32_e32 v88, 16, v45
	v_pk_fma_f32 v[76:77], v[24:25], v[84:85], v[130:131]
	v_pk_fma_f32 v[78:79], v[26:27], v[86:87], v[132:133]
	v_pk_fma_f32 v[80:81], v[28:29], v[42:43], v[134:135]
	v_pk_fma_f32 v[82:83], v[30:31], v[88:89], v[136:137]
	v_pk_fma_f32 v[44:45], v[16:17], v[84:85], v[90:91]
	v_and_b32_e32 v115, 0xffff0000, v46
	v_lshlrev_b32_e32 v114, 16, v46
	v_pk_fma_f32 v[90:91], v[18:19], v[86:87], v[120:121]
	v_and_b32_e32 v121, 0xffff0000, v47
	v_lshlrev_b32_e32 v120, 16, v47
	v_pk_fma_f32 v[46:47], v[20:21], v[42:43], v[122:123]
	v_and_b32_e32 v123, 0xffff0000, v48
	v_lshlrev_b32_e32 v122, 16, v48
	v_pk_fma_f32 v[96:97], v[22:23], v[88:89], v[96:97]
	v_and_b32_e32 v131, 0xffff0000, v49
	v_lshlrev_b32_e32 v130, 16, v49
	v_pk_fma_f32 v[48:49], v[8:9], v[84:85], v[98:99]
	v_pk_fma_f32 v[98:99], v[10:11], v[86:87], v[104:105]
	v_pk_fma_f32 v[104:105], v[12:13], v[42:43], v[106:107]
	v_pk_fma_f32 v[106:107], v[14:15], v[88:89], v[112:113]
	v_pk_fma_f32 v[112:113], v[0:1], v[84:85], v[32:33]
	v_pk_fma_f32 v[132:133], v[2:3], v[86:87], v[34:35]
	v_pk_fma_f32 v[42:43], v[4:5], v[42:43], v[36:37]
	v_pk_fma_f32 v[134:135], v[6:7], v[88:89], v[38:39]
	v_mul_f32_e32 v41, 0xbfb8aa3b, v76
	v_mul_f32_e32 v138, 0xbfb8aa3b, v77
	v_mul_f32_e32 v139, 0xbfb8aa3b, v78
	v_mul_f32_e32 v140, 0xbfb8aa3b, v79
	v_mul_f32_e32 v141, 0xbfb8aa3b, v80
	v_mul_f32_e32 v142, 0xbfb8aa3b, v81
	v_mul_f32_e32 v143, 0xbfb8aa3b, v82
	v_mul_f32_e32 v144, 0xbfb8aa3b, v83
	v_pk_fma_f32 v[84:85], v[24:25], v[114:115], v[44:45]
	v_pk_fma_f32 v[86:87], v[26:27], v[120:121], v[90:91]
	v_pk_fma_f32 v[88:89], v[28:29], v[122:123], v[46:47]
	v_pk_fma_f32 v[90:91], v[30:31], v[130:131], v[96:97]
	v_pk_fma_f32 v[44:45], v[16:17], v[114:115], v[48:49]
	v_and_b32_e32 v47, 0xffff0000, v92
	v_lshlrev_b32_e32 v46, 16, v92
	v_pk_fma_f32 v[48:49], v[18:19], v[120:121], v[98:99]
	v_and_b32_e32 v137, 0xffff0000, v93
	v_lshlrev_b32_e32 v136, 16, v93
	v_pk_fma_f32 v[96:97], v[20:21], v[122:123], v[104:105]
	v_and_b32_e32 v105, 0xffff0000, v94
	v_lshlrev_b32_e32 v104, 16, v94
	v_pk_fma_f32 v[98:99], v[22:23], v[130:131], v[106:107]
	v_and_b32_e32 v107, 0xffff0000, v95
	v_lshlrev_b32_e32 v106, 16, v95
	v_pk_fma_f32 v[112:113], v[8:9], v[114:115], v[112:113]
	v_pk_fma_f32 v[132:133], v[10:11], v[120:121], v[132:133]
	v_pk_fma_f32 v[42:43], v[12:13], v[122:123], v[42:43]
	v_pk_fma_f32 v[134:135], v[14:15], v[130:131], v[134:135]
	v_pk_fma_f32 v[114:115], v[0:1], v[114:115], v[32:33]
	v_pk_fma_f32 v[120:121], v[2:3], v[120:121], v[34:35]
	v_pk_fma_f32 v[122:123], v[4:5], v[122:123], v[36:37]
	v_pk_fma_f32 v[130:131], v[6:7], v[130:131], v[38:39]
	v_exp_f32_e32 v41, v41
	v_exp_f32_e32 v162, v138
	v_exp_f32_e32 v163, v139
	v_exp_f32_e32 v164, v140
	v_exp_f32_e32 v165, v141
	v_exp_f32_e32 v166, v142
	v_exp_f32_e32 v167, v143
	v_exp_f32_e32 v168, v144
	v_mul_f32_e32 v146, 0xbfb8aa3b, v84
	v_mul_f32_e32 v147, 0xbfb8aa3b, v85
	v_mul_f32_e32 v148, 0xbfb8aa3b, v86
	v_mul_f32_e32 v149, 0xbfb8aa3b, v87
	v_mul_f32_e32 v150, 0xbfb8aa3b, v88
	v_mul_f32_e32 v151, 0xbfb8aa3b, v89
	v_mul_f32_e32 v152, 0xbfb8aa3b, v90
	v_mul_f32_e32 v153, 0xbfb8aa3b, v91
	v_pk_fma_f32 v[92:93], v[24:25], v[46:47], v[44:45]
	v_pk_fma_f32 v[94:95], v[26:27], v[136:137], v[48:49]
	v_pk_fma_f32 v[96:97], v[28:29], v[104:105], v[96:97]
	v_pk_fma_f32 v[98:99], v[30:31], v[106:107], v[98:99]
	v_pk_fma_f32 v[44:45], v[16:17], v[46:47], v[112:113]
	v_and_b32_e32 v49, 0xffff0000, v100
	v_lshlrev_b32_e32 v48, 16, v100
	v_pk_fma_f32 v[112:113], v[18:19], v[136:137], v[132:133]
	v_and_b32_e32 v133, 0xffff0000, v101
	v_lshlrev_b32_e32 v132, 16, v101
	v_pk_fma_f32 v[42:43], v[20:21], v[104:105], v[42:43]
	v_and_b32_e32 v139, 0xffff0000, v102
	v_lshlrev_b32_e32 v138, 16, v102
	v_pk_fma_f32 v[134:135], v[22:23], v[106:107], v[134:135]
	v_and_b32_e32 v141, 0xffff0000, v103
	v_lshlrev_b32_e32 v140, 16, v103
	v_pk_fma_f32 v[114:115], v[8:9], v[46:47], v[114:115]
	v_pk_fma_f32 v[120:121], v[10:11], v[136:137], v[120:121]
	v_pk_fma_f32 v[122:123], v[12:13], v[104:105], v[122:123]
	v_pk_fma_f32 v[130:131], v[14:15], v[106:107], v[130:131]
	v_pk_fma_f32 v[46:47], v[0:1], v[46:47], v[32:33]
	v_pk_fma_f32 v[136:137], v[2:3], v[136:137], v[34:35]
	v_pk_fma_f32 v[142:143], v[4:5], v[104:105], v[36:37]
	v_pk_fma_f32 v[144:145], v[6:7], v[106:107], v[38:39]
	v_exp_f32_e32 v169, v146
	v_exp_f32_e32 v170, v147
	v_exp_f32_e32 v171, v148
	v_exp_f32_e32 v172, v149
; __device__ __forceinline__ float bf2f(unsigned short h) { return __uint_as_float(((unsigned)h) << 16); }
; __device__ __forceinline__ float silu_f(float x) { return x * __builtin_amdgcn_rcpf(1.f + __expf(-x)); }
; __device__ __forceinline__ void p2a_conv(const Args& A, int G) {
;     ...
;         for (int ii = 0; ii < 8; ++ii) { const int i = i0 + ii; const bf16x8 r3 = rr[ii]; float o[8];
; #pragma unroll
;             for (int e = 0; e < 8; ++e) { const float a = bs[e] + w[0][e] * bf2f((unsigned short)r0[e]) + w[1][e] * bf2f((unsigned short)r1[e]) + w[2][e] * bf2f((unsigned short)r2[e]) + w[3][e] * bf2f((unsigned short)r3[e]); o[e] = silu_f(a); }
	v_exp_f32_e32 v173, v150
	v_exp_f32_e32 v174, v151
	v_exp_f32_e32 v175, v152
	v_exp_f32_e32 v176, v153
	v_mul_f32_e32 v146, 0xbfb8aa3b, v92
	v_mul_f32_e32 v147, 0xbfb8aa3b, v93
	v_mul_f32_e32 v148, 0xbfb8aa3b, v94
	v_mul_f32_e32 v149, 0xbfb8aa3b, v95
	v_mul_f32_e32 v150, 0xbfb8aa3b, v96
	v_mul_f32_e32 v151, 0xbfb8aa3b, v97
	v_mul_f32_e32 v152, 0xbfb8aa3b, v98
	v_mul_f32_e32 v153, 0xbfb8aa3b, v99
	v_pk_fma_f32 v[100:101], v[24:25], v[48:49], v[44:45]
	v_pk_fma_f32 v[102:103], v[26:27], v[132:133], v[112:113]
	v_pk_fma_f32 v[104:105], v[28:29], v[138:139], v[42:43]
	v_pk_fma_f32 v[106:107], v[30:31], v[140:141], v[134:135]
	v_pk_fma_f32 v[42:43], v[16:17], v[48:49], v[114:115]
	v_and_b32_e32 v45, 0xffff0000, v108
	v_lshlrev_b32_e32 v44, 16, v108
	v_pk_fma_f32 v[112:113], v[18:19], v[132:133], v[120:121]
	v_and_b32_e32 v121, 0xffff0000, v109
	v_lshlrev_b32_e32 v120, 16, v109
	v_pk_fma_f32 v[114:115], v[20:21], v[138:139], v[122:123]
	v_and_b32_e32 v123, 0xffff0000, v110
	v_lshlrev_b32_e32 v122, 16, v110
	v_pk_fma_f32 v[130:131], v[22:23], v[140:141], v[130:131]
	v_and_b32_e32 v135, 0xffff0000, v111
	v_lshlrev_b32_e32 v134, 16, v111
	v_pk_fma_f32 v[46:47], v[8:9], v[48:49], v[46:47]
	v_pk_fma_f32 v[136:137], v[10:11], v[132:133], v[136:137]
	v_pk_fma_f32 v[142:143], v[12:13], v[138:139], v[142:143]
	v_pk_fma_f32 v[144:145], v[14:15], v[140:141], v[144:145]
	v_pk_fma_f32 v[48:49], v[0:1], v[48:49], v[32:33]
	v_pk_fma_f32 v[132:133], v[2:3], v[132:133], v[34:35]
	v_pk_fma_f32 v[138:139], v[4:5], v[138:139], v[36:37]
	v_pk_fma_f32 v[140:141], v[6:7], v[140:141], v[38:39]
	v_exp_f32_e32 v177, v146
	v_exp_f32_e32 v178, v147
	v_exp_f32_e32 v179, v148
	v_exp_f32_e32 v180, v149
	v_exp_f32_e32 v181, v150
	v_exp_f32_e32 v182, v151
	v_exp_f32_e32 v183, v152
	v_exp_f32_e32 v184, v153
	v_mul_f32_e32 v158, 0xbfb8aa3b, v100
	v_mul_f32_e32 v159, 0xbfb8aa3b, v101
	v_mul_f32_e32 v160, 0xbfb8aa3b, v102
	v_mul_f32_e32 v161, 0xbfb8aa3b, v103
	v_mul_f32_e32 v185, 0xbfb8aa3b, v104
	v_mul_f32_e32 v186, 0xbfb8aa3b, v105
	v_mul_f32_e32 v187, 0xbfb8aa3b, v106
	v_mul_f32_e32 v188, 0xbfb8aa3b, v107
	v_pk_fma_f32 v[108:109], v[24:25], v[44:45], v[42:43]
	v_pk_fma_f32 v[110:111], v[26:27], v[120:121], v[112:113]
	v_pk_fma_f32 v[112:113], v[28:29], v[122:123], v[114:115]
	v_pk_fma_f32 v[114:115], v[30:31], v[134:135], v[130:131]
	v_pk_fma_f32 v[46:47], v[16:17], v[44:45], v[46:47]
	v_and_b32_e32 v131, 0xffff0000, v116
	v_lshlrev_b32_e32 v130, 16, v116
	v_pk_fma_f32 v[136:137], v[18:19], v[120:121], v[136:137]
	v_and_b32_e32 v147, 0xffff0000, v117
	v_lshlrev_b32_e32 v146, 16, v117
	v_pk_fma_f32 v[142:143], v[20:21], v[122:123], v[142:143]
	v_and_b32_e32 v149, 0xffff0000, v118
	v_lshlrev_b32_e32 v148, 16, v118
	v_pk_fma_f32 v[144:145], v[22:23], v[134:135], v[144:145]
	v_and_b32_e32 v151, 0xffff0000, v119
	v_lshlrev_b32_e32 v150, 16, v119
	v_pk_fma_f32 v[48:49], v[8:9], v[44:45], v[48:49]
	v_pk_fma_f32 v[132:133], v[10:11], v[120:121], v[132:133]
	v_pk_fma_f32 v[138:139], v[12:13], v[122:123], v[138:139]
	v_pk_fma_f32 v[140:141], v[14:15], v[134:135], v[140:141]
	v_pk_fma_f32 v[152:153], v[0:1], v[44:45], v[32:33]
	v_pk_fma_f32 v[154:155], v[2:3], v[120:121], v[34:35]
	v_pk_fma_f32 v[156:157], v[4:5], v[122:123], v[36:37]
	v_pk_fma_f32 v[134:135], v[6:7], v[134:135], v[38:39]
	v_mov_b64_e32 v[42:43], v[116:117]
	v_mov_b64_e32 v[44:45], v[118:119]
	v_exp_f32_e32 v189, v158
	v_exp_f32_e32 v190, v159
	v_exp_f32_e32 v191, v160
	v_exp_f32_e32 v192, v161
	v_exp_f32_e32 v185, v185
	v_exp_f32_e32 v186, v186
	v_exp_f32_e32 v187, v187
	v_exp_f32_e32 v188, v188
	v_mul_f32_e32 v193, 0xbfb8aa3b, v108
	v_mul_f32_e32 v194, 0xbfb8aa3b, v109
	v_mul_f32_e32 v195, 0xbfb8aa3b, v110
	v_mul_f32_e32 v196, 0xbfb8aa3b, v111
	v_mul_f32_e32 v197, 0xbfb8aa3b, v112
	v_mul_f32_e32 v198, 0xbfb8aa3b, v113
	v_mul_f32_e32 v199, 0xbfb8aa3b, v114
	v_mul_f32_e32 v200, 0xbfb8aa3b, v115
	v_pk_fma_f32 v[116:117], v[24:25], v[130:131], v[46:47]
	v_pk_fma_f32 v[118:119], v[26:27], v[146:147], v[136:137]
	v_pk_fma_f32 v[120:121], v[28:29], v[148:149], v[142:143]
	v_pk_fma_f32 v[122:123], v[30:31], v[150:151], v[144:145]
	v_pk_fma_f32 v[136:137], v[16:17], v[130:131], v[48:49]
	v_and_b32_e32 v143, 0xffff0000, v126
	v_lshlrev_b32_e32 v142, 16, v126
	v_pk_fma_f32 v[132:133], v[18:19], v[146:147], v[132:133]
	v_and_b32_e32 v145, 0xffff0000, v127
	v_lshlrev_b32_e32 v144, 16, v127
	v_pk_fma_f32 v[138:139], v[20:21], v[148:149], v[138:139]
	v_and_b32_e32 v159, 0xffff0000, v128
	v_lshlrev_b32_e32 v158, 16, v128
	v_pk_fma_f32 v[140:141], v[22:23], v[150:151], v[140:141]
	v_and_b32_e32 v161, 0xffff0000, v129
	v_lshlrev_b32_e32 v160, 16, v129
	v_pk_fma_f32 v[130:131], v[8:9], v[130:131], v[152:153]
	v_pk_fma_f32 v[146:147], v[10:11], v[146:147], v[154:155]
	v_pk_fma_f32 v[148:149], v[12:13], v[148:149], v[156:157]
	v_pk_fma_f32 v[134:135], v[14:15], v[150:151], v[134:135]
	v_mov_b64_e32 v[46:47], v[126:127]
	v_mov_b64_e32 v[48:49], v[128:129]
	v_add_f32_e32 v41, 1.0, v41
	v_add_f32_e32 v151, 1.0, v162
	v_add_f32_e32 v152, 1.0, v163
	v_add_f32_e32 v153, 1.0, v164
	v_add_f32_e32 v154, 1.0, v165
	v_add_f32_e32 v155, 1.0, v166
	v_add_f32_e32 v156, 1.0, v167
	v_add_f32_e32 v157, 1.0, v168
	v_exp_f32_e32 v193, v193
	v_exp_f32_e32 v194, v194
	v_exp_f32_e32 v195, v195
	v_exp_f32_e32 v196, v196
	v_exp_f32_e32 v197, v197
	v_exp_f32_e32 v198, v198
	v_exp_f32_e32 v199, v199
	v_exp_f32_e32 v200, v200
	v_mul_f32_e32 v162, 0xbfb8aa3b, v116
	v_mul_f32_e32 v163, 0xbfb8aa3b, v117
	v_mul_f32_e32 v164, 0xbfb8aa3b, v118
	v_mul_f32_e32 v165, 0xbfb8aa3b, v119
	v_mul_f32_e32 v166, 0xbfb8aa3b, v120
	v_mul_f32_e32 v167, 0xbfb8aa3b, v121
; __device__ __forceinline__ unsigned pk2(float lo, float hi) { f32x2_c v = {lo, hi}; return __builtin_bit_cast(unsigned, __builtin_convertvector(v, bf16x2_c)); }
; __device__ __forceinline__ float bf2f(unsigned short h) { return __uint_as_float(((unsigned)h) << 16); }
; __device__ __forceinline__ float silu_f(float x) { return x * __builtin_amdgcn_rcpf(1.f + __expf(-x)); }
; __device__ __forceinline__ void p2a_conv(const Args& A, int G) {
;     ...
;         for (int ii = 0; ii < 8; ++ii) { const int i = i0 + ii; const bf16x8 r3 = rr[ii]; float o[8];
; #pragma unroll
;             for (int e = 0; e < 8; ++e) { const float a = bs[e] + w[0][e] * bf2f((unsigned short)r0[e]) + w[1][e] * bf2f((unsigned short)r1[e]) + w[2][e] * bf2f((unsigned short)r2[e]) + w[3][e] * bf2f((unsigned short)r3[e]); o[e] = silu_f(a); }
;             v4u pw; pw.x = pk2(o[0], o[1]); pw.y = pk2(o[2], o[3]); pw.z = pk2(o[4], o[5]); pw.w = pk2(o[6], o[7]);
	v_mul_f32_e32 v168, 0xbfb8aa3b, v122
	v_mul_f32_e32 v201, 0xbfb8aa3b, v123
	v_pk_fma_f32 v[126:127], v[24:25], v[142:143], v[136:137]
	v_pk_fma_f32 v[128:129], v[26:27], v[144:145], v[132:133]
	v_pk_fma_f32 v[132:133], v[28:29], v[158:159], v[138:139]
	v_pk_fma_f32 v[136:137], v[30:31], v[160:161], v[140:141]
	v_pk_fma_f32 v[130:131], v[16:17], v[142:143], v[130:131]
	v_and_b32_e32 v139, 0xffff0000, v50
	v_lshlrev_b32_e32 v138, 16, v50
	v_pk_fma_f32 v[140:141], v[18:19], v[144:145], v[146:147]
	v_and_b32_e32 v143, 0xffff0000, v51
	v_lshlrev_b32_e32 v142, 16, v51
	v_pk_fma_f32 v[144:145], v[20:21], v[158:159], v[148:149]
	v_and_b32_e32 v147, 0xffff0000, v52
	v_lshlrev_b32_e32 v146, 16, v52
	v_pk_fma_f32 v[134:135], v[22:23], v[160:161], v[134:135]
	v_and_b32_e32 v149, 0xffff0000, v53
	v_lshlrev_b32_e32 v148, 16, v53
	v_rcp_f32_e32 v150, v41
	v_rcp_f32_e32 v151, v151
	v_rcp_f32_e32 v152, v152
	v_rcp_f32_e32 v153, v153
	v_rcp_f32_e32 v154, v154
	v_rcp_f32_e32 v155, v155
	v_rcp_f32_e32 v156, v156
	v_rcp_f32_e32 v157, v157
	v_add_f32_e32 v41, 1.0, v169
	v_add_f32_e32 v158, 1.0, v170
	v_add_f32_e32 v159, 1.0, v171
	v_add_f32_e32 v160, 1.0, v172
	v_add_f32_e32 v161, 1.0, v173
	v_add_f32_e32 v169, 1.0, v174
	v_add_f32_e32 v170, 1.0, v175
	v_add_f32_e32 v171, 1.0, v176
	v_exp_f32_e32 v174, v162
	v_exp_f32_e32 v175, v163
	v_exp_f32_e32 v176, v164
	v_exp_f32_e32 v202, v165
	v_exp_f32_e32 v203, v166
	v_exp_f32_e32 v204, v167
	v_exp_f32_e32 v205, v168
	v_exp_f32_e32 v201, v201
	v_mul_f32_e32 v162, 0xbfb8aa3b, v126
	v_mul_f32_e32 v163, 0xbfb8aa3b, v127
	v_mul_f32_e32 v164, 0xbfb8aa3b, v128
	v_mul_f32_e32 v165, 0xbfb8aa3b, v129
	v_mul_f32_e32 v166, 0xbfb8aa3b, v132
	v_mul_f32_e32 v167, 0xbfb8aa3b, v133
	v_mul_f32_e32 v168, 0xbfb8aa3b, v136
	v_mul_f32_e32 v172, 0xbfb8aa3b, v137
	v_pk_fma_f32 v[130:131], v[24:25], v[138:139], v[130:131]
	v_pk_fma_f32 v[138:139], v[26:27], v[142:143], v[140:141]
	v_pk_fma_f32 v[140:141], v[28:29], v[146:147], v[144:145]
	v_pk_fma_f32 v[134:135], v[30:31], v[148:149], v[134:135]
	v_rcp_f32_e32 v142, v41
	v_rcp_f32_e32 v143, v158
	v_rcp_f32_e32 v144, v159
	v_rcp_f32_e32 v145, v160
	v_rcp_f32_e32 v146, v161
	v_rcp_f32_e32 v147, v169
	v_rcp_f32_e32 v148, v170
	v_rcp_f32_e32 v149, v171
	v_add_f32_e32 v41, 1.0, v177
	v_add_f32_e32 v159, 1.0, v178
	v_add_f32_e32 v160, 1.0, v179
	v_add_f32_e32 v161, 1.0, v180
	v_add_f32_e32 v169, 1.0, v181
	v_add_f32_e32 v170, 1.0, v182
	v_add_f32_e32 v171, 1.0, v183
	v_add_f32_e32 v173, 1.0, v184
	v_exp_f32_e32 v177, v162
	v_exp_f32_e32 v178, v163
	v_exp_f32_e32 v179, v164
	v_exp_f32_e32 v180, v165
	v_exp_f32_e32 v181, v166
	v_exp_f32_e32 v182, v167
	v_exp_f32_e32 v183, v168
	v_exp_f32_e32 v184, v172
	v_mul_f32_e32 v166, 0xbfb8aa3b, v130
	v_mul_f32_e32 v167, 0xbfb8aa3b, v131
	v_mul_f32_e32 v168, 0xbfb8aa3b, v138
	v_mul_f32_e32 v172, 0xbfb8aa3b, v139
	v_mul_f32_e32 v206, 0xbfb8aa3b, v140
	v_mul_f32_e32 v207, 0xbfb8aa3b, v141
	v_mul_f32_e32 v208, 0xbfb8aa3b, v134
	v_mul_f32_e32 v209, 0xbfb8aa3b, v135
	v_rcp_f32_e32 v158, v41
	v_rcp_f32_e32 v159, v159
	v_rcp_f32_e32 v160, v160
	v_rcp_f32_e32 v161, v161
	v_rcp_f32_e32 v162, v169
	v_rcp_f32_e32 v163, v170
	v_rcp_f32_e32 v164, v171
	v_rcp_f32_e32 v165, v173
	v_add_f32_e32 v41, 1.0, v189
	v_add_f32_e32 v169, 1.0, v190
	v_add_f32_e32 v170, 1.0, v191
	v_add_f32_e32 v171, 1.0, v192
	v_add_f32_e32 v173, 1.0, v185
	v_add_f32_e32 v185, 1.0, v186
	v_add_f32_e32 v186, 1.0, v187
	v_add_f32_e32 v187, 1.0, v188
	v_exp_f32_e32 v188, v166
	v_exp_f32_e32 v189, v167
	v_exp_f32_e32 v190, v168
	v_exp_f32_e32 v191, v172
	v_exp_f32_e32 v192, v206
	v_exp_f32_e32 v206, v207
	v_exp_f32_e32 v207, v208
	v_exp_f32_e32 v208, v209
	v_rcp_f32_e32 v166, v41
	v_rcp_f32_e32 v167, v169
	v_rcp_f32_e32 v168, v170
	v_rcp_f32_e32 v169, v171
	v_rcp_f32_e32 v170, v173
	v_rcp_f32_e32 v171, v185
	v_rcp_f32_e32 v172, v186
	v_rcp_f32_e32 v173, v187
	v_add_f32_e32 v41, 1.0, v193
	v_add_f32_e32 v185, 1.0, v194
	v_add_f32_e32 v186, 1.0, v195
	v_add_f32_e32 v187, 1.0, v196
	v_add_f32_e32 v193, 1.0, v197
	v_add_f32_e32 v194, 1.0, v198
	v_add_f32_e32 v195, 1.0, v199
	v_add_f32_e32 v196, 1.0, v200
	v_pk_mul_f32 v[76:77], v[76:77], v[150:151]
	v_pk_mul_f32 v[78:79], v[78:79], v[152:153]
	v_pk_mul_f32 v[80:81], v[80:81], v[154:155]
	v_pk_mul_f32 v[82:83], v[82:83], v[156:157]
	v_rcp_f32_e32 v150, v41
	v_rcp_f32_e32 v151, v185
; __device__ __forceinline__ unsigned pk2(float lo, float hi) { f32x2_c v = {lo, hi}; return __builtin_bit_cast(unsigned, __builtin_convertvector(v, bf16x2_c)); }
; __device__ __forceinline__ float bf2f(unsigned short h) { return __uint_as_float(((unsigned)h) << 16); }
; __device__ __forceinline__ float silu_f(float x) { return x * __builtin_amdgcn_rcpf(1.f + __expf(-x)); }
; __device__ __forceinline__ void p2a_conv(const Args& A, int G) {
;     ...
;             for (int e = 0; e < 8; ++e) { const float a = bs[e] + w[0][e] * bf2f((unsigned short)r0[e]) + w[1][e] * bf2f((unsigned short)r1[e]) + w[2][e] * bf2f((unsigned short)r2[e]) + w[3][e] * bf2f((unsigned short)r3[e]); o[e] = silu_f(a); }
;             v4u pw; pw.x = pk2(o[0], o[1]); pw.y = pk2(o[2], o[3]); pw.z = pk2(o[4], o[5]); pw.w = pk2(o[6], o[7]);
;             *(v4u*)(XC + (size_t)(m0 + i) * 2048 + ch) = pw; r0 = r1; r1 = r2; r2 = r3; } }
;     }
	v_rcp_f32_e32 v152, v186
	v_rcp_f32_e32 v153, v187
	v_rcp_f32_e32 v154, v193
	v_rcp_f32_e32 v155, v194
	v_rcp_f32_e32 v156, v195
	v_rcp_f32_e32 v157, v196
	v_add_f32_e32 v41, 1.0, v174
	v_add_f32_e32 v174, 1.0, v175
	v_add_f32_e32 v175, 1.0, v176
	v_add_f32_e32 v176, 1.0, v202
	v_add_f32_e32 v185, 1.0, v203
	v_add_f32_e32 v186, 1.0, v204
	v_add_f32_e32 v187, 1.0, v205
	v_add_f32_e32 v193, 1.0, v201
	v_cvt_pk_bf16_f32 v76, v76, v77
	v_cvt_pk_bf16_f32 v77, v78, v79
	v_cvt_pk_bf16_f32 v78, v80, v81
	v_cvt_pk_bf16_f32 v79, v82, v83
	v_pk_mul_f32 v[80:81], v[84:85], v[142:143]
	v_pk_mul_f32 v[82:83], v[86:87], v[144:145]
	v_pk_mul_f32 v[84:85], v[88:89], v[146:147]
	v_pk_mul_f32 v[86:87], v[90:91], v[148:149]
	v_rcp_f32_e32 v88, v41
	v_rcp_f32_e32 v89, v174
	v_rcp_f32_e32 v90, v175
	v_rcp_f32_e32 v91, v176
	v_rcp_f32_e32 v142, v185
	v_rcp_f32_e32 v143, v186
	v_rcp_f32_e32 v144, v187
	v_rcp_f32_e32 v145, v193
	v_add_f32_e32 v41, 1.0, v177
	v_add_f32_e32 v146, 1.0, v178
	v_add_f32_e32 v147, 1.0, v179
	v_add_f32_e32 v148, 1.0, v180
	v_add_f32_e32 v149, 1.0, v181
	v_add_f32_e32 v174, 1.0, v182
	v_add_f32_e32 v175, 1.0, v183
	v_add_f32_e32 v176, 1.0, v184
	global_store_dwordx4 v[74:75], v[76:79], off
	v_cvt_pk_bf16_f32 v74, v80, v81
	v_cvt_pk_bf16_f32 v75, v82, v83
	v_cvt_pk_bf16_f32 v76, v84, v85
	v_cvt_pk_bf16_f32 v77, v86, v87
	v_pk_mul_f32 v[78:79], v[92:93], v[158:159]
	v_pk_mul_f32 v[80:81], v[94:95], v[160:161]
	v_pk_mul_f32 v[82:83], v[96:97], v[162:163]
	v_pk_mul_f32 v[84:85], v[98:99], v[164:165]
	v_rcp_f32_e32 v86, v41
	v_rcp_f32_e32 v87, v146
	v_rcp_f32_e32 v92, v147
	v_rcp_f32_e32 v93, v148
	v_rcp_f32_e32 v94, v149
	v_rcp_f32_e32 v95, v174
	v_rcp_f32_e32 v96, v175
	v_rcp_f32_e32 v97, v176
	v_add_f32_e32 v41, 1.0, v188
	v_add_f32_e32 v98, 1.0, v189
	v_add_f32_e32 v99, 1.0, v190
	v_add_f32_e32 v146, 1.0, v191
	v_add_f32_e32 v147, 1.0, v192
	v_add_f32_e32 v148, 1.0, v206
	v_add_f32_e32 v149, 1.0, v207
	v_add_f32_e32 v158, 1.0, v208
	global_store_dwordx4 v[72:73], v[74:77], off
	v_cvt_pk_bf16_f32 v72, v78, v79
	v_cvt_pk_bf16_f32 v73, v80, v81
	v_cvt_pk_bf16_f32 v74, v82, v83
	v_cvt_pk_bf16_f32 v75, v84, v85
	v_pk_mul_f32 v[76:77], v[100:101], v[166:167]
	v_pk_mul_f32 v[78:79], v[102:103], v[168:169]
	v_pk_mul_f32 v[80:81], v[104:105], v[170:171]
	v_pk_mul_f32 v[82:83], v[106:107], v[172:173]
	v_rcp_f32_e32 v84, v41
	v_rcp_f32_e32 v85, v98
	v_rcp_f32_e32 v98, v99
	v_rcp_f32_e32 v99, v146
	v_rcp_f32_e32 v100, v147
	v_rcp_f32_e32 v101, v148
	v_rcp_f32_e32 v102, v149
	v_rcp_f32_e32 v103, v158
	global_store_dwordx4 v[70:71], v[72:75], off
	v_cvt_pk_bf16_f32 v70, v76, v77
	v_cvt_pk_bf16_f32 v71, v78, v79
	v_cvt_pk_bf16_f32 v72, v80, v81
	v_cvt_pk_bf16_f32 v73, v82, v83
	v_pk_mul_f32 v[74:75], v[108:109], v[150:151]
	v_pk_mul_f32 v[76:77], v[110:111], v[152:153]
	v_pk_mul_f32 v[78:79], v[112:113], v[154:155]
	v_pk_mul_f32 v[80:81], v[114:115], v[156:157]
	global_store_dwordx4 v[68:69], v[70:73], off
	v_cvt_pk_bf16_f32 v68, v74, v75
	v_cvt_pk_bf16_f32 v69, v76, v77
	v_cvt_pk_bf16_f32 v70, v78, v79
	v_cvt_pk_bf16_f32 v71, v80, v81
	v_pk_mul_f32 v[72:73], v[116:117], v[88:89]
	v_pk_mul_f32 v[74:75], v[118:119], v[90:91]
	v_pk_mul_f32 v[76:77], v[120:121], v[142:143]
	v_pk_mul_f32 v[78:79], v[122:123], v[144:145]
	global_store_dwordx4 v[66:67], v[68:71], off
	v_cvt_pk_bf16_f32 v66, v72, v73
	v_cvt_pk_bf16_f32 v67, v74, v75
	v_cvt_pk_bf16_f32 v68, v76, v77
	v_cvt_pk_bf16_f32 v69, v78, v79
	v_pk_mul_f32 v[70:71], v[126:127], v[86:87]
	v_pk_mul_f32 v[72:73], v[128:129], v[92:93]
	v_pk_mul_f32 v[74:75], v[132:133], v[94:95]
	v_pk_mul_f32 v[76:77], v[136:137], v[96:97]
	global_store_dwordx4 v[64:65], v[66:69], off
	v_cvt_pk_bf16_f32 v64, v70, v71
	v_cvt_pk_bf16_f32 v65, v72, v73
	v_cvt_pk_bf16_f32 v66, v74, v75
	v_cvt_pk_bf16_f32 v67, v76, v77
	v_pk_mul_f32 v[68:69], v[130:131], v[84:85]
	v_pk_mul_f32 v[70:71], v[138:139], v[98:99]
	v_pk_mul_f32 v[72:73], v[140:141], v[100:101]
	v_pk_mul_f32 v[74:75], v[134:135], v[102:103]
	global_store_dwordx4 v[62:63], v[64:67], off
	v_cvt_pk_bf16_f32 v62, v68, v69
	v_cvt_pk_bf16_f32 v63, v70, v71
	v_cvt_pk_bf16_f32 v64, v72, v73
	v_cvt_pk_bf16_f32 v65, v74, v75
	global_store_dwordx4 v[60:61], v[62:65], off
	s_cbranch_scc0 .LBB0_603
	s_add_i32 s3, s3, s38
	s_cmpk_gt_i32 s3, 0xff
	v_add_u32_e32 v125, s0, v125
	s_cbranch_scc0 .LBB0_600
